# loop-edge edit: attention tile loop back edge is the conditional branch itself (one branch per tile), loop head 64-byte aligned; on top of v118
# speedup vs baseline: 1.0091x; 1.0091x over previous
.LBB0_531:
	s_lshl_b32 s0, s14, 2
	s_and_b32 s0, s0, 28
	v_sub_u32_e64 v2, s0, 1 clamp
	s_add_i32 s42, s12, s0
	s_max_u32 s43, s0, 4
	v_readfirstlane_b32 s0, v2
	s_bfe_u32 s71, s14, 0x40003
	s_min_u32 s0, s0, 24
	s_ashr_i32 s40, s14, 7
	s_sub_i32 s72, s0, s43
	s_lshl_b32 s0, s71, 8
	s_add_u32 s8, s68, s0
	s_addc_u32 s9, s69, 0
	s_add_u32 s10, s66, s0
	s_addc_u32 s11, s67, 0
	s_ashr_i32 s41, s40, 31
	s_lshl_b64 s[18:19], s[40:41], 11
	s_lshl_b32 s33, s42, 6
	s_add_u32 s18, s18, s33
	s_addc_u32 s19, s19, 0
	v_mov_b32_e32 v155, s19
	v_or_b32_e32 v154, s18, v146
	s_waitcnt lgkmcnt(0)
	v_lshlrev_b64 v[2:3], 12, v[154:155]
	s_lshl_b32 s18, s40, 8
	v_lshl_add_u64 v[2:3], s[20:21], 0, v[2:3]
	s_add_i32 s38, s18, 0x2000
	v_lshl_add_u64 v[2:3], v[2:3], 0, s[0:1]
	s_ashr_i32 s39, s38, 31
	v_lshl_add_u64 v[2:3], v[2:3], 0, v[152:153]
	s_lshl_b64 s[74:75], s[38:39], 12
	s_ashr_i32 s19, s18, 31
	global_load_dwordx4 v[82:85], v[2:3], off nt
	global_load_dwordx4 v[86:89], v[2:3], off offset:32 nt
	global_load_dwordx4 v[90:93], v[2:3], off offset:64 nt
	global_load_dwordx4 v[94:97], v[2:3], off offset:96 nt
	global_load_dwordx4 v[98:101], v[2:3], off offset:128 nt
	global_load_dwordx4 v[102:105], v[2:3], off offset:160 nt
	global_load_dwordx4 v[106:109], v[2:3], off offset:192 nt
	global_load_dwordx4 v[110:113], v[2:3], off offset:224 nt
	v_lshl_add_u64 v[2:3], s[74:75], 0, v[148:149]
	s_lshl_b64 s[18:19], s[18:19], 12
	s_mov_b32 m0, s15
	v_lshl_add_u64 v[4:5], s[10:11], 0, v[2:3]
	s_add_u32 s74, s18, 0x2020000
	global_load_lds_dwordx4 v[4:5], off
	v_lshl_add_u64 v[2:3], s[8:9], 0, v[2:3]
	s_mov_b32 m0, s24
	s_addc_u32 s75, s19, 0
	global_load_lds_dwordx4 v[2:3], off
	v_lshl_add_u64 v[2:3], s[74:75], 0, v[148:149]
	v_lshl_add_u64 v[4:5], s[10:11], 0, v[2:3]
	s_mov_b32 m0, s25
	s_add_u32 s74, s18, 0x2040000
	global_load_lds_dwordx4 v[4:5], off
	v_lshl_add_u64 v[2:3], s[8:9], 0, v[2:3]
	s_mov_b32 m0, s35
	s_addc_u32 s75, s19, 0
	global_load_lds_dwordx4 v[2:3], off
	v_lshl_add_u64 v[2:3], s[74:75], 0, v[148:149]
	v_lshl_add_u64 v[4:5], s[10:11], 0, v[2:3]
	s_mov_b32 m0, s46
	s_add_u32 s74, s18, 0x2060000
	global_load_lds_dwordx4 v[4:5], off
	v_lshl_add_u64 v[2:3], s[8:9], 0, v[2:3]
	s_mov_b32 m0, s47
	s_addc_u32 s75, s19, 0
	global_load_lds_dwordx4 v[2:3], off
	v_lshl_add_u64 v[2:3], s[74:75], 0, v[148:149]
	v_lshl_add_u64 v[4:5], s[10:11], 0, v[2:3]
	s_mov_b32 m0, s57
	s_add_u32 s18, s18, 0x2080000
	global_load_lds_dwordx4 v[4:5], off
	v_lshl_add_u64 v[2:3], s[8:9], 0, v[2:3]
	s_mov_b32 m0, s60
	s_addc_u32 s19, s19, 0
	global_load_lds_dwordx4 v[2:3], off
	v_lshl_add_u64 v[2:3], s[18:19], 0, v[148:149]
	v_lshl_add_u64 v[4:5], s[10:11], 0, v[2:3]
	s_mov_b32 m0, s61
	v_lshl_add_u64 v[2:3], s[8:9], 0, v[2:3]
	s_mov_b32 m0, s63
	s_cmp_lt_i32 s72, -15
	s_cbranch_scc1 .LBB0_547
	s_max_i32 s0, s42, 4
	s_add_i32 s0, s0, -4
	s_mul_i32 s18, s71, 15
	s_min_u32 s0, s0, 24
	s_sub_i32 s18, s18, s42
	s_add_i32 s18, s18, s0
	v_mov_b32_e32 v50, v151
	v_mov_b32_e32 v51, v151
	s_lshl_b32 s72, s72, 1
	s_mulk_i32 s18, 0x7c
	v_mov_b32_e32 v52, v151
	v_mov_b32_e32 v53, v151
	v_mov_b32_e32 v54, v151
	v_mov_b32_e32 v55, v151
	v_mov_b32_e32 v56, v151
	v_mov_b32_e32 v57, v151
	v_mov_b32_e32 v58, v151
	v_mov_b32_e32 v59, v151
	v_mov_b32_e32 v60, v151
	v_mov_b32_e32 v61, v151
	v_mov_b32_e32 v62, v151
	v_mov_b32_e32 v63, v151
	v_mov_b32_e32 v64, v151
	v_mov_b32_e32 v65, v151
	v_mov_b64_e32 v[34:35], v[50:51]
	v_mov_b64_e32 v[18:19], v[50:51]
	v_mov_b64_e32 v[2:3], v[50:51]
	s_add_i32 s39, s43, -4
	s_add_i32 s72, s72, 31
	s_lshl_b32 s73, s40, 11
	s_add_i32 s74, s0, 8
	v_add_u32_e32 v176, s18, v172
	s_mov_b32 s75, 0
	s_mov_b32 s76, 4
	v_mov_b32_e32 v177, 0xff800000
	v_mov_b32_e32 v175, 0
	v_mov_b64_e32 v[36:37], v[52:53]
	v_mov_b64_e32 v[38:39], v[54:55]
	v_mov_b64_e32 v[40:41], v[56:57]
	v_mov_b64_e32 v[42:43], v[58:59]
	v_mov_b64_e32 v[44:45], v[60:61]
	v_mov_b64_e32 v[46:47], v[62:63]
	v_mov_b64_e32 v[48:49], v[64:65]
	v_mov_b64_e32 v[20:21], v[52:53]
	v_mov_b64_e32 v[22:23], v[54:55]
	v_mov_b64_e32 v[24:25], v[56:57]
	v_mov_b64_e32 v[26:27], v[58:59]
	v_mov_b64_e32 v[28:29], v[60:61]
	v_mov_b64_e32 v[30:31], v[62:63]
	v_mov_b64_e32 v[32:33], v[64:65]
	v_mov_b64_e32 v[4:5], v[52:53]
	v_mov_b64_e32 v[6:7], v[54:55]
	v_mov_b64_e32 v[8:9], v[56:57]
	v_mov_b64_e32 v[10:11], v[58:59]
	v_mov_b64_e32 v[12:13], v[60:61]
	v_mov_b64_e32 v[14:15], v[62:63]
	v_mov_b64_e32 v[16:17], v[64:65]
	s_mov_b32 s77, 0
	s_mov_b32 s78, 0
	s_mov_b32 s100, s38
	s_lshl_b32 s101, s39, 6
	s_add_i32 s101, s101, s73
	s_addk_i32 s101, 0xff00
	s_waitcnt vmcnt(0)
	.p2align 6

.LBB0_545:
	s_add_i32 s18, s77, 1
	s_cmp_lg_u32 s18, 6
	s_cselect_b32 s77, s18, 0
	s_add_i32 s18, s76, 1
	s_cmp_lg_u32 s18, 6
	s_cselect_b32 s76, s18, 0
	s_add_i32 s75, s75, 32
	s_add_i32 s40, s78, 1
	s_cmp_lg_u32 s78, s72
	s_cselect_b32 s78, s40, s78
	s_cbranch_scc1 .LBB0_533
	s_branch .LBB0_548
